# baseline (speedup 1.0000x reference)
; template <int MODE>
; __device__ __forceinline__ void attn_item(const Params& P, int b, int h, int qb, char* lds) {
;     ...
;       if (MODE == 1) {
;         const float* cb = cs_l + buf * 64 + 4 * hi;
;         const float cref = c2t - m_reg;
; #pragma unroll
;         for (int q = 0; q < 4; ++q) {
;           const f32x4 ca = *(const f32x4*)(cb + 8 * q), cc = *(const f32x4*)(cb + 32 + 8 * q);
; #pragma unroll
;           for (int e = 0; e < 4; ++e) { p0[q * 4 + e] = cref - ca[e]; p1[q * 4 + e] = cref - cc[e]; }
;         }
;       } else {
;         const float nref = -m_reg;
; #pragma unroll
;         for (int r = 0; r < 16; ++r) { p0[r] = nref; p1[r] = nref; }
;       }
;       {
;         const char* kbp = K_lds + buf * 16384;
; #pragma unroll
;         for (int d0 = 0; d0 < 8; ++d0) {
;           const char* a = kbp + KSWZ(r32, (d0 * 16 + hi * 8) * 2);
;           const bf16x8 b0 = *(const bf16x8*)a;
;           const bf16x8 b1 = *(const bf16x8*)(a + 32 * 256);
;           p0 = __builtin_amdgcn_mfma_f32_32x32x16_bf16(b0, qr[d0], p0, 0, 0, 0);
;           p1 = __builtin_amdgcn_mfma_f32_32x32x16_bf16(b1, qr[d0], p1, 0, 0, 0);
;         }
;       }
.LBB0_1024:
	s_add_i32 s2, s72, s75
	s_add_i32 s3, s2, 0xc0
	s_cmp_gt_i32 s3, s74
	s_cbranch_scc1 .LBB0_1017
	v_lshl_add_u32 v0, s9, 8, v177
	s_lshl_b32 s9, s9, 14
	v_sub_f32_e32 v14, v173, v193
	ds_read_b128 v[2:5], v0
	ds_read_b128 v[6:9], v0 offset:32
	ds_read_b128 v[10:13], v0 offset:64
	ds_read_b128 v[96:99], v0 offset:96
	ds_read_b128 v[112:115], v0 offset:128
	ds_read_b128 v[116:119], v0 offset:160
	ds_read_b128 v[120:123], v0 offset:192
	ds_read_b128 v[124:127], v0 offset:224
	v_add_u32_e32 v0, s9, v178
	v_add_u32_e32 v251, v0, v181
	ds_read_b128 v[194:197], v251 offset:32768
	ds_read_b128 v[226:229], v251 offset:40960
	v_add_u32_e32 v252, v0, v182
	ds_read_b128 v[198:201], v252 offset:32768
	ds_read_b128 v[230:233], v252 offset:40960
	v_add_u32_e32 v253, v0, v183
	ds_read_b128 v[202:205], v253 offset:32768
	ds_read_b128 v[234:237], v253 offset:40960
	s_waitcnt lgkmcnt(6)
	v_sub_f32_e32 v100, v14, v6
	v_sub_f32_e32 v111, v14, v99
	v_sub_f32_e32 v110, v14, v98
	v_sub_f32_e32 v109, v14, v97
	v_sub_f32_e32 v108, v14, v96
	v_sub_f32_e32 v103, v14, v9
	v_sub_f32_e32 v102, v14, v8
	v_sub_f32_e32 v101, v14, v7
	v_sub_f32_e32 v99, v14, v5
	v_sub_f32_e32 v98, v14, v4
	v_sub_f32_e32 v97, v14, v3
	v_sub_f32_e32 v96, v14, v2
	v_sub_f32_e32 v107, v14, v13
	v_sub_f32_e32 v106, v14, v12
	v_sub_f32_e32 v105, v14, v11
	v_sub_f32_e32 v104, v14, v10
	v_sub_f32_e32 v127, v14, v127
	v_sub_f32_e32 v126, v14, v126
	v_sub_f32_e32 v125, v14, v125
	v_sub_f32_e32 v124, v14, v124
	v_sub_f32_e32 v123, v14, v123
	v_sub_f32_e32 v122, v14, v122
	v_sub_f32_e32 v121, v14, v121
	v_sub_f32_e32 v120, v14, v120
	v_sub_f32_e32 v119, v14, v119
	v_sub_f32_e32 v118, v14, v118
	v_sub_f32_e32 v117, v14, v117
	v_sub_f32_e32 v116, v14, v116
	v_sub_f32_e32 v115, v14, v115
	v_sub_f32_e32 v114, v14, v114
	v_sub_f32_e32 v113, v14, v113
	v_sub_f32_e32 v112, v14, v112
	s_addk_i32 s2, 0xff
	s_cmp_le_i32 s2, s71
	s_waitcnt lgkmcnt(5)
	v_mfma_f32_32x32x16_bf16 v[96:111], v[194:197], v[128:131], v[96:111]
	v_add_u32_e32 v251, v0, v186
	ds_read_b128 v[206:209], v251 offset:32768
	ds_read_b128 v[238:241], v251 offset:40960
	s_waitcnt lgkmcnt(6)
	v_mfma_f32_32x32x16_bf16 v[112:127], v[226:229], v[128:131], v[112:127]
	v_add_u32_e32 v252, v0, v187
	ds_read_b128 v[210:213], v252 offset:32768
	ds_read_b128 v[242:245], v252 offset:40960
	s_waitcnt lgkmcnt(7)
	v_mfma_f32_32x32x16_bf16 v[96:111], v[198:201], v[132:135], v[96:111]
	v_add_u32_e32 v253, v0, v188
	ds_read_b128 v[214:217], v253 offset:32768
	ds_read_b128 v[246:249], v253 offset:40960
	s_waitcnt lgkmcnt(8)
	v_mfma_f32_32x32x16_bf16 v[112:127], v[230:233], v[132:135], v[112:127]
	v_add_u32_e32 v251, v0, v189
	ds_read_b128 v[218:221], v251 offset:32768
	ds_read_b128 v[2:5], v251 offset:40960
	s_waitcnt lgkmcnt(9)
	v_mfma_f32_32x32x16_bf16 v[96:111], v[202:205], v[136:139], v[96:111]
	v_add_u32_e32 v252, v0, v190
	ds_read_b128 v[222:225], v252 offset:32768
	ds_read_b128 v[6:9], v252 offset:40960
	s_waitcnt lgkmcnt(10)
	v_mfma_f32_32x32x16_bf16 v[112:127], v[234:237], v[136:139], v[112:127]
	s_waitcnt lgkmcnt(9)
	v_mfma_f32_32x32x16_bf16 v[96:111], v[206:209], v[140:143], v[96:111]
	s_waitcnt lgkmcnt(8)
	v_mfma_f32_32x32x16_bf16 v[112:127], v[238:241], v[140:143], v[112:127]
	s_waitcnt lgkmcnt(7)
	v_mfma_f32_32x32x16_bf16 v[96:111], v[210:213], v[144:147], v[96:111]
	s_waitcnt lgkmcnt(6)
	v_mfma_f32_32x32x16_bf16 v[112:127], v[242:245], v[144:147], v[112:127]
	s_waitcnt lgkmcnt(5)
	v_mfma_f32_32x32x16_bf16 v[96:111], v[214:217], v[148:151], v[96:111]
	s_waitcnt lgkmcnt(4)
	v_mfma_f32_32x32x16_bf16 v[112:127], v[246:249], v[148:151], v[112:127]
	s_waitcnt lgkmcnt(3)
	v_mfma_f32_32x32x16_bf16 v[96:111], v[218:221], v[152:155], v[96:111]
	s_waitcnt lgkmcnt(2)
	v_mfma_f32_32x32x16_bf16 v[112:127], v[2:5], v[152:155], v[112:127]
	s_waitcnt lgkmcnt(1)
	v_mfma_f32_32x32x16_bf16 v[96:111], v[222:225], v[156:159], v[96:111]
	s_waitcnt lgkmcnt(0)
	v_mfma_f32_32x32x16_bf16 v[112:127], v[6:9], v[156:159], v[112:127]
	s_cbranch_scc1 .LBB0_1027
; template <int MODE>
; __device__ __forceinline__ void attn_item(const Params& P, int b, int h, int qb, char* lds) {
;     ...
;         if (kb + 63 > q0) {
;           const int dq = qpos - kb - 4 * hi;
; #pragma unroll
;           for (int r = 0; r < 16; ++r) {
;             const int c = (r & 3) + 8 * (r >> 2);
;             if (dq - c < 0) p0[r] = NEG;
;             if (dq - c - 32 < 0) p1[r] = NEG;
;           }
;         }
	v_add_u32_e32 v0, s0, v192
	v_add_u32_e32 v2, 0xffffff40, v0
	v_cmp_lt_i32_e32 vcc, -1, v2
	s_nop 6
	v_cndmask_b32_e32 v96, v170, v96, vcc
	v_cmp_lt_i32_e32 vcc, 31, v2
	v_add_u32_e32 v2, 0xffffff3f, v0
	s_nop 0
	v_cndmask_b32_e32 v112, v170, v112, vcc
	v_cmp_lt_i32_e32 vcc, -1, v2
	s_nop 1
	v_cndmask_b32_e32 v97, v170, v97, vcc
	v_cmp_lt_i32_e32 vcc, 31, v2
	v_add_u32_e32 v2, 0xffffff3e, v0
	s_nop 0
	v_cndmask_b32_e32 v113, v170, v113, vcc
	v_cmp_lt_i32_e32 vcc, -1, v2
	s_nop 1
	v_cndmask_b32_e32 v98, v170, v98, vcc
	v_cmp_lt_i32_e32 vcc, 31, v2
	v_add_u32_e32 v2, 0xffffff3d, v0
	s_nop 0
	v_cndmask_b32_e32 v114, v170, v114, vcc
	v_cmp_lt_i32_e32 vcc, -1, v2
	s_nop 1
	v_cndmask_b32_e32 v99, v170, v99, vcc
	v_cmp_lt_i32_e32 vcc, 31, v2
	v_add_u32_e32 v2, 0xffffff38, v0
	s_nop 0
	v_cndmask_b32_e32 v115, v170, v115, vcc
	v_cmp_lt_i32_e32 vcc, -1, v2
	s_nop 1
	v_cndmask_b32_e32 v100, v170, v100, vcc
	v_cmp_lt_i32_e32 vcc, 31, v2
	v_add_u32_e32 v2, 0xffffff37, v0
	s_nop 0
	v_cndmask_b32_e32 v116, v170, v116, vcc
	v_cmp_lt_i32_e32 vcc, -1, v2
	s_nop 1
	v_cndmask_b32_e32 v101, v170, v101, vcc
	v_cmp_lt_i32_e32 vcc, 31, v2
	v_add_u32_e32 v2, 0xffffff36, v0
	s_nop 0
	v_cndmask_b32_e32 v117, v170, v117, vcc
	v_cmp_lt_i32_e32 vcc, -1, v2
	s_nop 1
	v_cndmask_b32_e32 v102, v170, v102, vcc
	v_cmp_lt_i32_e32 vcc, 31, v2
	v_add_u32_e32 v2, 0xffffff35, v0
	s_nop 0
	v_cndmask_b32_e32 v118, v170, v118, vcc
	v_cmp_lt_i32_e32 vcc, -1, v2
	s_nop 1
	v_cndmask_b32_e32 v103, v170, v103, vcc
	v_cmp_lt_i32_e32 vcc, 31, v2
	v_add_u32_e32 v2, 0xffffff30, v0
	s_nop 0
	v_cndmask_b32_e32 v119, v170, v119, vcc
	v_cmp_lt_i32_e32 vcc, -1, v2
	s_nop 1
	v_cndmask_b32_e32 v104, v170, v104, vcc
	v_cmp_lt_i32_e32 vcc, 31, v2
	v_add_u32_e32 v2, 0xffffff2f, v0
	s_nop 0
	v_cndmask_b32_e32 v120, v170, v120, vcc
	v_cmp_lt_i32_e32 vcc, -1, v2
	s_nop 1
	v_cndmask_b32_e32 v105, v170, v105, vcc
	v_cmp_lt_i32_e32 vcc, 31, v2
	v_add_u32_e32 v2, 0xffffff2e, v0
	s_nop 0
	v_cndmask_b32_e32 v121, v170, v121, vcc
	v_cmp_lt_i32_e32 vcc, -1, v2
	s_nop 1
	v_cndmask_b32_e32 v106, v170, v106, vcc
	v_cmp_lt_i32_e32 vcc, 31, v2
	v_add_u32_e32 v2, 0xffffff2d, v0
	s_nop 0
	v_cndmask_b32_e32 v122, v170, v122, vcc
	v_cmp_lt_i32_e32 vcc, -1, v2
	s_nop 1
	v_cndmask_b32_e32 v107, v170, v107, vcc
	v_cmp_lt_i32_e32 vcc, 31, v2
	v_add_u32_e32 v2, 0xffffff28, v0
	s_nop 0
	v_cndmask_b32_e32 v123, v170, v123, vcc
	v_cmp_lt_i32_e32 vcc, -1, v2
	s_nop 1
	v_cndmask_b32_e32 v108, v170, v108, vcc
	v_cmp_lt_i32_e32 vcc, 31, v2
	v_add_u32_e32 v2, 0xffffff27, v0
	s_nop 0
	v_cndmask_b32_e32 v124, v170, v124, vcc
	v_cmp_lt_i32_e32 vcc, -1, v2
	s_nop 1
	v_cndmask_b32_e32 v109, v170, v109, vcc
	v_cmp_lt_i32_e32 vcc, 31, v2
	v_add_u32_e32 v2, 0xffffff26, v0
	v_add_u32_e32 v0, 0xffffff25, v0
	v_cndmask_b32_e32 v125, v170, v125, vcc
	v_cmp_lt_i32_e32 vcc, -1, v2
	s_nop 1
	v_cndmask_b32_e32 v110, v170, v110, vcc
	v_cmp_lt_i32_e32 vcc, 31, v2
	s_nop 1
	v_cndmask_b32_e32 v126, v170, v126, vcc
	v_cmp_lt_i32_e32 vcc, -1, v0
	s_nop 1
	v_cndmask_b32_e32 v111, v170, v111, vcc
	v_cmp_lt_i32_e32 vcc, 31, v0
	s_nop 1
	v_cndmask_b32_e32 v127, v170, v127, vcc

; __global__ void __launch_bounds__(NTH, 2) fwd_megakernel(Params P) {
	.amdhsa_kernel _Z14fwd_megakernel6Params
		.amdhsa_group_segment_fixed_size 16
		.amdhsa_private_segment_fixed_size 0
		.amdhsa_kernarg_size 368
		.amdhsa_user_sgpr_count 2
		.amdhsa_user_sgpr_dispatch_ptr 0
		.amdhsa_user_sgpr_queue_ptr 0
		.amdhsa_user_sgpr_kernarg_segment_ptr 1
		.amdhsa_user_sgpr_dispatch_id 0
		.amdhsa_user_sgpr_kernarg_preload_length 0
		.amdhsa_user_sgpr_kernarg_preload_offset 0
		.amdhsa_user_sgpr_private_segment_size 0
		.amdhsa_uses_dynamic_stack 0
		.amdhsa_enable_private_segment 0
		.amdhsa_system_sgpr_workgroup_id_x 1
		.amdhsa_system_sgpr_workgroup_id_y 0
		.amdhsa_system_sgpr_workgroup_id_z 0
		.amdhsa_system_sgpr_workgroup_info 0
		.amdhsa_system_vgpr_workitem_id 2
		.amdhsa_next_free_vgpr 256
		.amdhsa_next_free_sgpr 102
		.amdhsa_accum_offset 256
		.amdhsa_reserve_vcc 1
		.amdhsa_float_round_mode_32 0
		.amdhsa_float_round_mode_16_64 0
		.amdhsa_float_denorm_mode_32 3
		.amdhsa_float_denorm_mode_16_64 3
		.amdhsa_dx10_clamp 1
		.amdhsa_ieee_mode 1
		.amdhsa_fp16_overflow 0
		.amdhsa_tg_split 0
		.amdhsa_exception_fp_ieee_invalid_op 0
		.amdhsa_exception_fp_denorm_src 0
		.amdhsa_exception_fp_ieee_div_zero 0
		.amdhsa_exception_fp_ieee_overflow 0
		.amdhsa_exception_fp_ieee_underflow 0
		.amdhsa_exception_fp_ieee_inexact 0
		.amdhsa_exception_int_div_zero 0
	.end_amdhsa_kernel

; __global__ void __launch_bounds__(NTH, 2) fwd_megakernel(Params P) {
amdhsa.kernels:
  - .agpr_count:     0
    .args:
      - .offset:         0
        .size:           112
        .value_kind:     by_value
      - .offset:         112
        .size:           4
        .value_kind:     hidden_block_count_x
      - .offset:         116
        .size:           4
        .value_kind:     hidden_block_count_y
      - .offset:         120
        .size:           4
        .value_kind:     hidden_block_count_z
      - .offset:         124
        .size:           2
        .value_kind:     hidden_group_size_x
      - .offset:         126
        .size:           2
        .value_kind:     hidden_group_size_y
      - .offset:         128
        .size:           2
        .value_kind:     hidden_group_size_z
      - .offset:         130
        .size:           2
        .value_kind:     hidden_remainder_x
      - .offset:         132
        .size:           2
        .value_kind:     hidden_remainder_y
      - .offset:         134
        .size:           2
        .value_kind:     hidden_remainder_z
      - .offset:         152
        .size:           8
        .value_kind:     hidden_global_offset_x
      - .offset:         160
        .size:           8
        .value_kind:     hidden_global_offset_y
      - .offset:         168
        .size:           8
        .value_kind:     hidden_global_offset_z
      - .offset:         176
        .size:           2
        .value_kind:     hidden_grid_dims
      - .offset:         200
        .size:           8
        .value_kind:     hidden_multigrid_sync_arg
      - .offset:         232
        .size:           4
        .value_kind:     hidden_dynamic_lds_size
    .group_segment_fixed_size: 16
    .kernarg_segment_align: 8
    .kernarg_segment_size: 368
    .language:       OpenCL C
    .language_version:
      - 2
      - 0
    .max_flat_workgroup_size: 512
    .name:           _Z14fwd_megakernel6Params
    .private_segment_fixed_size: 0
    .sgpr_count:     108
    .sgpr_spill_count: 63
    .symbol:         _Z14fwd_megakernel6Params.kd
    .uniform_work_group_size: 1
    .uses_dynamic_stack: false
    .vgpr_count:     256
    .vgpr_spill_count: 0
    .wavefront_size: 64
